# v6: + batched SB softplus with non-diagonal fast path, SB/light queue rebalance, SB V-fragment reads hoisted
# speedup vs baseline: 1.0525x; 1.0018x over previous
; __global__ void __launch_bounds__(512) fwd_megakernel(Args a) {
;     ...
;             if (tq0_ == 0) { int slot = -1;
;                 while (tries < 8) { int len = (myq < 4) ? 64 : 192;
;     ...
;                     if (rep) len = 64;
;     ...
;                     if (rep) { if (myq < 4) len = 0; }
;     ...
;  const int idx = (int)atomicAdd(barw + BAR_QCTR + 64 * myq, 1u);
;     ...
;                     if (rep && myq >= 4 && idx < 64) continue;
;     ...
;                     if (idx < len) { slot = (myq << 16) | idx; break; } myq = (myq + 1) & 7; ++tries; }
.LBB0_350:
	v_cmp_gt_i32_e32 vcc, 8, v239
	s_or_b64 s[24:25], s[24:25], exec
	s_and_saveexec_b64 s[26:27], vcc
	s_cbranch_execz .LBB0_349
	v_readlane_b32 s12, v254, 56
	v_lshlrev_b32_e32 v0, 6, v233
	v_readlane_b32 s13, v254, 57
	v_cmp_gt_i32_e32 vcc, 4, v233
	s_nop 0
	v_lshl_add_u64 v[4:5], v[0:1], 2, s[12:13]
	global_atomic_add v0, v[4:5], v231, off sc0
	v_and_b32_e32 v3, 1, v233
	v_lshlrev_b32_e32 v3, 6, v3
	v_add_u32_e32 v3, 0xa0, v3
	v_cndmask_b32_e64 v3, v3, 64, vcc
	s_waitcnt vmcnt(0)
	v_cmp_ge_i32_e32 vcc, v0, v3
	s_and_saveexec_b64 s[12:13], vcc
	s_xor_b64 s[36:37], exec, s[12:13]
	v_add_u32_e32 v4, 1, v233
	v_and_b32_e32 v233, 7, v4
	v_add_u32_e32 v239, 1, v239
	s_andn2_saveexec_b64 s[36:37], s[36:37]
	s_cbranch_execz .LBB0_348
	v_lshl_or_b32 v2, v233, 16, v0
	s_branch .LBB0_348

; __global__ void __launch_bounds__(512) fwd_megakernel(Args a) {
;     ...
;             const int q = slot >> 16, idx = slot & 0xffff;
;             int ub, uh, uq; bool isdf = true;
;             if (q < 4) { ub = q >> 1; uh = 3 - (q & 1); uq = 63 - idx; }
;             else { const int y = q - 4;
;                 if (idx < 64) { ub = y >> 1; uh = 1 - (y & 1); uq = 63 - idx; }
;                 else { const int v = idx - 64; const int bh = 4 * y + (v & 3); ub = bh >> 3; uh = bh & 7; uq = 31 - (v >> 2); isdf = false; } }
.LBB0_356:
	s_or_b64 exec, exec, s[0:1]
	s_add_i32 s0, s4, 0
	v_mov_b32_e32 v0, s0
	s_waitcnt lgkmcnt(0)
	s_barrier
	ds_read_b32 v0, v0
	s_waitcnt lgkmcnt(0)
	v_cmp_gt_i32_e32 vcc, 0, v0
	v_readfirstlane_b32 s4, v0
	s_cbranch_vccnz .LBB0_370
	s_and_b32 s5, s4, 0xffff
	s_cmp_gt_u32 s4, 0x3ffff
	s_mov_b64 s[6:7], -1
	s_cbranch_scc0 .LBB0_367
	s_lshr_b32 s12, s4, 16
	s_add_i32 s12, s12, -4
	s_cmp_lt_u32 s5, 64
	s_cselect_b64 s[0:1], -1, 0
	s_cmp_gt_u32 s5, 63
	s_cbranch_scc0 .LBB0_360
	s_sub_i32 s6, s5, 64
	s_cmp_lt_u32 s6, 0x80
	s_cbranch_scc1 .Lsbq_own
	s_add_i32 s12, s12, -1
	s_add_i32 s6, s6, -32
.Lsbq_own:
	s_lshl_b32 s7, s12, 2
	s_and_b32 s13, s4, 3
	s_and_b32 s7, s7, 4
	s_lshr_b32 s6, s6, 2
	s_or_b32 s16, s7, s13
	s_sub_i32 s15, 31, s6
	s_mov_b64 s[6:7], 0

; #define MFMA32(a, b, c) __builtin_amdgcn_mfma_f32_32x32x16_bf16((a), (b), (c), 0, 0, 0)
; DI int crow(int r, int hi) { return (r & 3) + 8 * (r >> 2) + 4 * hi; }
; DI float ex2(float x) { return __builtin_amdgcn_exp2f(x); }
; DI float lg2(float x) { return __builtin_amdgcn_logf(x); }
; DI void sb_unit(LAS char* lds, int b, int h, int qb, const bf16_t* __restrict__ Q, const bf16_t* __restrict__ K, const bf16_t* __restrict__ VT, const bf16_t* __restrict__ G, bf16_t* __restrict__ MIX) {
;     ...
;         if (kv0 < qw0 + 31 && !done) {
;             f32x16 p0 = splat16(0.f), p1 = splat16(0.f);
; #pragma unroll
;             for (int d0 = 0; d0 < 4; ++d0) { const bf16x8 k0 = ldsv(Kt + off128(r32, 2 * d0 + hi)), k1 = ldsv(Kt + off128(32 + r32, 2 * d0 + hi)); p0 = MFMA32(k0, qf[d0], p0); p1 = MFMA32(k1, qf[d0], p1); }
;             const bool diag = (kv0 + 63 >= qw0);
;             f32x16 L0, L1;
; #pragma unroll
;             for (int r = 0; r < 16; ++r) {
;                 { const float z = p0[r]; const float lg = (z > 30.f) ? z : lg2(1.0f + ex2(z)); const bool valid = !diag || (kv0 + crow(r, hi) < tq); L0[r] = valid ? -lg : 0.f; p0[r] = valid ? (z - lg) : -1e30f; }
.LBB0_422:
	s_and_b32 s42, s38, 1
	s_cmp_ge_i32 s39, s26
	s_cselect_b64 s[0:1], -1, 0
	v_cmp_ne_u32_e32 vcc, 0, v36
	s_or_b64 s[0:1], s[0:1], vcc
	s_and_b64 vcc, exec, s[0:1]
	s_cbranch_vccnz .LBB0_424
	s_lshl_b32 s0, s42, 14
	s_add_i32 s43, s0, 0
	v_add_u32_e32 v35, s43, v103
	v_add_u32_e32 v40, v35, v104
	ds_read_b128 v[36:39], v40
	ds_read_b128 v[40:43], v40 offset:4096
	v_add_u32_e32 v112, v35, v105
	ds_read_b128 v[108:111], v112
	ds_read_b128 v[112:115], v112 offset:4096
	s_add_i32 s0, s39, 63
	s_waitcnt vmcnt(3) lgkmcnt(3)
	v_mfma_f32_32x32x16_bf16 v[52:67], v[36:39], v[68:71], 0
	s_cmp_lt_i32 s0, s24
	s_cselect_b64 s[0:1], -1, 0
	v_readlane_b32 s4, v254, 48
	v_readlane_b32 s6, v254, 50
	v_readlane_b32 s7, v254, 51
	v_readlane_b32 s5, v254, 49
	s_mov_b32 s6, s4
	s_waitcnt lgkmcnt(2)
	v_mfma_f32_32x32x16_bf16 v[36:51], v[40:43], v[68:71], 0
	s_mov_b32 s7, s4
	s_mov_b32 s5, s4
	s_waitcnt vmcnt(2) lgkmcnt(1)
	v_mfma_f32_32x32x16_bf16 v[52:67], v[108:111], v[72:75], v[52:67]
	s_waitcnt lgkmcnt(0)
	v_mfma_f32_32x32x16_bf16 v[36:51], v[112:115], v[72:75], v[36:51]
	v_add_u32_e32 v112, v35, v106
	ds_read_b128 v[108:111], v112
	ds_read_b128 v[112:115], v112 offset:4096
	v_add_u32_e32 v35, v35, v107
	s_waitcnt vmcnt(1) lgkmcnt(1)
	v_mfma_f32_32x32x16_bf16 v[52:67], v[108:111], v[76:79], v[52:67]
	s_waitcnt lgkmcnt(0)
	v_mfma_f32_32x32x16_bf16 v[36:51], v[112:115], v[76:79], v[36:51]
	ds_read_b128 v[108:111], v35
	ds_read_b128 v[112:115], v35 offset:4096
	v_add_u32_e32 v35, s39, v102
	v_add_u32_e32 v133, 24, v35
	v_add_u32_e32 v138, 58, v35
	s_waitcnt vmcnt(0) lgkmcnt(1)
	v_mfma_f32_32x32x16_bf16 v[52:67], v[108:111], v[80:83], v[52:67]
	v_add_u32_e32 v110, 32, v35
	s_waitcnt lgkmcnt(0)
	v_mfma_f32_32x32x16_bf16 v[36:51], v[112:115], v[80:83], v[36:51]
	s_nop 8
	v_exp_f32_e32 v160, v52
	v_exp_f32_e32 v161, v53
	v_exp_f32_e32 v162, v54
	v_exp_f32_e32 v163, v55
	v_exp_f32_e32 v164, v56
	v_exp_f32_e32 v165, v57
	v_exp_f32_e32 v166, v58
	v_exp_f32_e32 v167, v59
	v_exp_f32_e32 v168, v60
	v_exp_f32_e32 v169, v61
	v_exp_f32_e32 v170, v62
	v_exp_f32_e32 v171, v63
	v_exp_f32_e32 v172, v64
	v_exp_f32_e32 v173, v65
	v_exp_f32_e32 v174, v66
	v_exp_f32_e32 v175, v67
	v_exp_f32_e32 v176, v36
	v_exp_f32_e32 v177, v37
	v_exp_f32_e32 v178, v38
	v_exp_f32_e32 v179, v39
	v_exp_f32_e32 v180, v40
	v_exp_f32_e32 v181, v41
	v_exp_f32_e32 v182, v42
	v_exp_f32_e32 v183, v43
	v_exp_f32_e32 v184, v44
	v_exp_f32_e32 v185, v45
	v_exp_f32_e32 v186, v46
	v_exp_f32_e32 v187, v47
	v_exp_f32_e32 v188, v48
	v_exp_f32_e32 v189, v49
	v_exp_f32_e32 v190, v50
	v_exp_f32_e32 v191, v51
	v_add_f32_e32 v160, 1.0, v160
	v_add_f32_e32 v161, 1.0, v161
	v_add_f32_e32 v162, 1.0, v162
	v_add_f32_e32 v163, 1.0, v163
	v_add_f32_e32 v164, 1.0, v164
	v_add_f32_e32 v165, 1.0, v165
	v_add_f32_e32 v166, 1.0, v166
	v_add_f32_e32 v167, 1.0, v167
	v_add_f32_e32 v168, 1.0, v168
	v_add_f32_e32 v169, 1.0, v169
	v_add_f32_e32 v170, 1.0, v170
	v_add_f32_e32 v171, 1.0, v171
	v_add_f32_e32 v172, 1.0, v172
	v_add_f32_e32 v173, 1.0, v173
	v_add_f32_e32 v174, 1.0, v174
	v_add_f32_e32 v175, 1.0, v175
	v_add_f32_e32 v176, 1.0, v176
	v_add_f32_e32 v177, 1.0, v177
	v_add_f32_e32 v178, 1.0, v178
	v_add_f32_e32 v179, 1.0, v179
	v_add_f32_e32 v180, 1.0, v180
	v_add_f32_e32 v181, 1.0, v181
	v_add_f32_e32 v182, 1.0, v182
	v_add_f32_e32 v183, 1.0, v183
	v_add_f32_e32 v184, 1.0, v184
	v_add_f32_e32 v185, 1.0, v185
	v_add_f32_e32 v186, 1.0, v186
	v_add_f32_e32 v187, 1.0, v187
	v_add_f32_e32 v188, 1.0, v188
	v_add_f32_e32 v189, 1.0, v189
	v_add_f32_e32 v190, 1.0, v190
	v_add_f32_e32 v191, 1.0, v191
	v_log_f32_e32 v160, v160
	v_log_f32_e32 v161, v161
	v_log_f32_e32 v162, v162
	v_log_f32_e32 v163, v163
	v_log_f32_e32 v164, v164
	v_log_f32_e32 v165, v165
	v_log_f32_e32 v166, v166
	v_log_f32_e32 v167, v167
	v_log_f32_e32 v168, v168
	v_log_f32_e32 v169, v169
	v_log_f32_e32 v170, v170
	v_log_f32_e32 v171, v171
	v_log_f32_e32 v172, v172
	v_log_f32_e32 v173, v173
	v_log_f32_e32 v174, v174
	v_log_f32_e32 v175, v175
	v_log_f32_e32 v176, v176
	v_log_f32_e32 v177, v177
	v_log_f32_e32 v178, v178
	v_log_f32_e32 v179, v179
	v_log_f32_e32 v180, v180
	v_log_f32_e32 v181, v181
	v_log_f32_e32 v182, v182
	v_log_f32_e32 v183, v183
	v_log_f32_e32 v184, v184
	v_log_f32_e32 v185, v185
	v_log_f32_e32 v186, v186
	v_log_f32_e32 v187, v187
	v_log_f32_e32 v188, v188
	v_log_f32_e32 v189, v189
	v_log_f32_e32 v190, v190
	v_log_f32_e32 v191, v191
	v_cmp_lt_f32_e64 s[52:53], s22, v52
	v_cmp_lt_f32_e64 s[54:55], s22, v53
	v_cmp_lt_f32_e64 s[56:57], s22, v54
	v_cmp_lt_f32_e64 s[58:59], s22, v55
	v_cmp_lt_f32_e64 s[60:61], s22, v56
	v_cmp_lt_f32_e64 s[62:63], s22, v57
	v_cmp_lt_f32_e64 s[64:65], s22, v58
	v_cmp_lt_f32_e64 s[66:67], s22, v59
	v_cmp_lt_f32_e64 s[68:69], s22, v60
	v_cmp_lt_f32_e64 s[70:71], s22, v61
	v_cndmask_b32_e64 v160, v160, v52, s[52:53]
	v_cndmask_b32_e64 v161, v161, v53, s[54:55]
	v_cndmask_b32_e64 v162, v162, v54, s[56:57]
	v_cndmask_b32_e64 v163, v163, v55, s[58:59]
	v_cndmask_b32_e64 v164, v164, v56, s[60:61]
	v_cndmask_b32_e64 v165, v165, v57, s[62:63]
	v_cndmask_b32_e64 v166, v166, v58, s[64:65]
	v_cndmask_b32_e64 v167, v167, v59, s[66:67]
	v_cndmask_b32_e64 v168, v168, v60, s[68:69]
	v_cndmask_b32_e64 v169, v169, v61, s[70:71]
	v_cmp_lt_f32_e64 s[52:53], s22, v62
	v_cmp_lt_f32_e64 s[54:55], s22, v63
	v_cmp_lt_f32_e64 s[56:57], s22, v64
	v_cmp_lt_f32_e64 s[58:59], s22, v65
	v_cmp_lt_f32_e64 s[60:61], s22, v66
	v_cmp_lt_f32_e64 s[62:63], s22, v67
	v_cmp_lt_f32_e64 s[64:65], s22, v36
	v_cmp_lt_f32_e64 s[66:67], s22, v37
	v_cmp_lt_f32_e64 s[68:69], s22, v38
	v_cmp_lt_f32_e64 s[70:71], s22, v39
	v_cndmask_b32_e64 v170, v170, v62, s[52:53]
; DI int crow(int r, int hi) { return (r & 3) + 8 * (r >> 2) + 4 * hi; }
; DI float ex2(float x) { return __builtin_amdgcn_exp2f(x); }
; DI float lg2(float x) { return __builtin_amdgcn_logf(x); }
; template <int S> DI bf16x8 pack8(const f32x16& x) { u32x4 p; p[0] = cvtpk(x[8 * S], x[8 * S + 1]); p[1] = cvtpk(x[8 * S + 2], x[8 * S + 3]); p[2] = cvtpk(x[8 * S + 4], x[8 * S + 5]); p[3] = cvtpk(x[8 * S + 6], x[8 * S + 7]); return __builtin_bit_cast(bf16x8, p); }
; DI void sb_unit(LAS char* lds, int b, int h, int qb, const bf16_t* __restrict__ Q, const bf16_t* __restrict__ K, const bf16_t* __restrict__ VT, const bf16_t* __restrict__ G, bf16_t* __restrict__ MIX) {
;     ...
;             const bool diag = (kv0 + 63 >= qw0);
;             f32x16 L0, L1;
; #pragma unroll
;             for (int r = 0; r < 16; ++r) {
;                 { const float z = p0[r]; const float lg = (z > 30.f) ? z : lg2(1.0f + ex2(z)); const bool valid = !diag || (kv0 + crow(r, hi) < tq); L0[r] = valid ? -lg : 0.f; p0[r] = valid ? (z - lg) : -1e30f; }
;                 { const float z = p1[r]; const float lg = (z > 30.f) ? z : lg2(1.0f + ex2(z)); const bool valid = !diag || (kv0 + 32 + crow(r, hi) < tq); L1[r] = valid ? -lg : 0.f; p1[r] = valid ? (z - lg) : -1e30f; }
;             }
;             const bf16x8 Lh0 = pack8<0>(L0), Lh1 = pack8<1>(L0), Lh2 = pack8<0>(L1), Lh3 = pack8<1>(L1);
	v_cndmask_b32_e64 v171, v171, v63, s[54:55]
	v_cndmask_b32_e64 v172, v172, v64, s[56:57]
	v_cndmask_b32_e64 v173, v173, v65, s[58:59]
	v_cndmask_b32_e64 v174, v174, v66, s[60:61]
	v_cndmask_b32_e64 v175, v175, v67, s[62:63]
	v_cndmask_b32_e64 v176, v176, v36, s[64:65]
	v_cndmask_b32_e64 v177, v177, v37, s[66:67]
	v_cndmask_b32_e64 v178, v178, v38, s[68:69]
	v_cndmask_b32_e64 v179, v179, v39, s[70:71]
	v_cmp_lt_f32_e64 s[52:53], s22, v40
	v_cmp_lt_f32_e64 s[54:55], s22, v41
	v_cmp_lt_f32_e64 s[56:57], s22, v42
	v_cmp_lt_f32_e64 s[58:59], s22, v43
	v_cmp_lt_f32_e64 s[60:61], s22, v44
	v_cmp_lt_f32_e64 s[62:63], s22, v45
	v_cmp_lt_f32_e64 s[64:65], s22, v46
	v_cmp_lt_f32_e64 s[66:67], s22, v47
	v_cmp_lt_f32_e64 s[68:69], s22, v48
	v_cmp_lt_f32_e64 s[70:71], s22, v49
	v_cndmask_b32_e64 v180, v180, v40, s[52:53]
	v_cndmask_b32_e64 v181, v181, v41, s[54:55]
	v_cndmask_b32_e64 v182, v182, v42, s[56:57]
	v_cndmask_b32_e64 v183, v183, v43, s[58:59]
	v_cndmask_b32_e64 v184, v184, v44, s[60:61]
	v_cndmask_b32_e64 v185, v185, v45, s[62:63]
	v_cndmask_b32_e64 v186, v186, v46, s[64:65]
	v_cndmask_b32_e64 v187, v187, v47, s[66:67]
	v_cndmask_b32_e64 v188, v188, v48, s[68:69]
	v_cndmask_b32_e64 v189, v189, v49, s[70:71]
	v_cmp_lt_f32_e64 s[52:53], s22, v50
	v_cmp_lt_f32_e64 s[54:55], s22, v51
	s_nop 1
	v_cndmask_b32_e64 v190, v190, v50, s[52:53]
	v_cndmask_b32_e64 v191, v191, v51, s[54:55]
	s_and_b64 vcc, exec, s[0:1]
	s_cbranch_vccz .Lsb_sp_diag
	v_sub_f32_e32 v109, 0, v160
	v_cvt_pk_bf16_f32 v138, -v160, -v161
	v_cvt_pk_bf16_f32 v139, -v162, -v163
	v_cvt_pk_bf16_f32 v140, -v164, -v165
	v_cvt_pk_bf16_f32 v141, -v166, -v167
	v_cvt_pk_bf16_f32 v142, -v168, -v169
	v_cvt_pk_bf16_f32 v143, -v170, -v171
	v_cvt_pk_bf16_f32 v144, -v172, -v173
	v_cvt_pk_bf16_f32 v145, -v174, -v175
	v_cvt_pk_bf16_f32 v146, -v176, -v177
	v_cvt_pk_bf16_f32 v147, -v178, -v179
	v_cvt_pk_bf16_f32 v148, -v180, -v181
	v_cvt_pk_bf16_f32 v149, -v182, -v183
	v_cvt_pk_bf16_f32 v150, -v184, -v185
	v_cvt_pk_bf16_f32 v151, -v186, -v187
	v_cvt_pk_bf16_f32 v152, -v188, -v189
	v_cvt_pk_bf16_f32 v153, -v190, -v191
	v_sub_f32_e32 v108, v52, v160
	v_sub_f32_e32 v111, v53, v161
	v_sub_f32_e32 v113, v54, v162
	v_sub_f32_e32 v115, v55, v163
	v_sub_f32_e32 v117, v56, v164
	v_sub_f32_e32 v119, v57, v165
	v_sub_f32_e32 v121, v58, v166
	v_sub_f32_e32 v123, v59, v167
	v_sub_f32_e32 v125, v60, v168
	v_sub_f32_e32 v127, v61, v169
	v_sub_f32_e32 v129, v62, v170
	v_sub_f32_e32 v131, v63, v171
	v_sub_f32_e32 v133, v64, v172
	v_sub_f32_e32 v135, v65, v173
	v_sub_f32_e32 v66, v66, v174
	v_sub_f32_e32 v155, v67, v175
	v_sub_f32_e32 v110, v36, v176
	v_sub_f32_e32 v112, v37, v177
	v_sub_f32_e32 v114, v38, v178
	v_sub_f32_e32 v116, v39, v179
	v_sub_f32_e32 v118, v40, v180
	v_sub_f32_e32 v120, v41, v181
	v_sub_f32_e32 v122, v42, v182
	v_sub_f32_e32 v124, v43, v183
	v_sub_f32_e32 v126, v44, v184
	v_sub_f32_e32 v128, v45, v185
	v_sub_f32_e32 v130, v46, v186
	v_sub_f32_e32 v132, v47, v187
	v_sub_f32_e32 v134, v48, v188
	v_sub_f32_e32 v136, v49, v189
	v_sub_f32_e32 v154, v50, v190
	v_sub_f32_e32 v156, v51, v191
	s_branch .Lsb_sp_join
.Lsb_sp_diag:
	v_cmp_lt_i32_e64 s[52:53], v35, v101
	v_add_u32_e32 v193, 1, v35
	v_add_u32_e32 v194, 2, v35
	v_add_u32_e32 v195, 3, v35
	v_add_u32_e32 v196, 8, v35
	v_add_u32_e32 v197, 9, v35
	v_add_u32_e32 v198, 10, v35
	v_add_u32_e32 v199, 11, v35
	v_add_u32_e32 v200, 16, v35
	v_add_u32_e32 v201, 17, v35
	v_cmp_lt_i32_e64 s[54:55], v193, v101
	v_cmp_lt_i32_e64 s[56:57], v194, v101
	v_cmp_lt_i32_e64 s[58:59], v195, v101
	v_cmp_lt_i32_e64 s[60:61], v196, v101
	v_cmp_lt_i32_e64 s[62:63], v197, v101
	v_cmp_lt_i32_e64 s[64:65], v198, v101
	v_cmp_lt_i32_e64 s[66:67], v199, v101
	v_cmp_lt_i32_e64 s[68:69], v200, v101
	v_cmp_lt_i32_e64 s[70:71], v201, v101
	v_cndmask_b32_e64 v192, 0, -v160, s[52:53]
	v_cndmask_b32_e64 v193, 0, -v161, s[54:55]
	v_cndmask_b32_e64 v194, 0, -v162, s[56:57]
	v_cndmask_b32_e64 v195, 0, -v163, s[58:59]
	v_cndmask_b32_e64 v196, 0, -v164, s[60:61]
	v_cndmask_b32_e64 v197, 0, -v165, s[62:63]
	v_cndmask_b32_e64 v198, 0, -v166, s[64:65]
	v_cndmask_b32_e64 v199, 0, -v167, s[66:67]
	v_cndmask_b32_e64 v200, 0, -v168, s[68:69]
	v_cndmask_b32_e64 v201, 0, -v169, s[70:71]
	v_sub_f32_e32 v160, v52, v160
	v_sub_f32_e32 v161, v53, v161
	v_sub_f32_e32 v162, v54, v162
	v_sub_f32_e32 v163, v55, v163
	v_sub_f32_e32 v164, v56, v164
	v_sub_f32_e32 v165, v57, v165
	v_sub_f32_e32 v166, v58, v166
	v_sub_f32_e32 v167, v59, v167
	v_sub_f32_e32 v168, v60, v168
	v_sub_f32_e32 v169, v61, v169
	v_cndmask_b32_e64 v108, v237, v160, s[52:53]
	v_cndmask_b32_e64 v111, v237, v161, s[54:55]
	v_cndmask_b32_e64 v113, v237, v162, s[56:57]
	v_cndmask_b32_e64 v115, v237, v163, s[58:59]
	v_cndmask_b32_e64 v117, v237, v164, s[60:61]
	v_cndmask_b32_e64 v119, v237, v165, s[62:63]
	v_cndmask_b32_e64 v121, v237, v166, s[64:65]
	v_cndmask_b32_e64 v123, v237, v167, s[66:67]
	v_cndmask_b32_e64 v125, v237, v168, s[68:69]
	v_cndmask_b32_e64 v127, v237, v169, s[70:71]
	v_add_u32_e32 v202, 18, v35
	v_add_u32_e32 v203, 19, v35
	v_add_u32_e32 v204, 24, v35
	v_add_u32_e32 v205, 25, v35
	v_add_u32_e32 v206, 26, v35
	v_add_u32_e32 v207, 27, v35
	v_add_u32_e32 v208, 32, v35
	v_add_u32_e32 v209, 33, v35
	v_add_u32_e32 v210, 34, v35
	v_add_u32_e32 v211, 35, v35
	v_cmp_lt_i32_e64 s[52:53], v202, v101
	v_cmp_lt_i32_e64 s[54:55], v203, v101
	v_cmp_lt_i32_e64 s[56:57], v204, v101
	v_cmp_lt_i32_e64 s[58:59], v205, v101
	v_cmp_lt_i32_e64 s[60:61], v206, v101
	v_cmp_lt_i32_e64 s[62:63], v207, v101
	v_cmp_lt_i32_e64 s[64:65], v208, v101
	v_cmp_lt_i32_e64 s[66:67], v209, v101
	v_cmp_lt_i32_e64 s[68:69], v210, v101
	v_cmp_lt_i32_e64 s[70:71], v211, v101
; DI int crow(int r, int hi) { return (r & 3) + 8 * (r >> 2) + 4 * hi; }
; DI float ex2(float x) { return __builtin_amdgcn_exp2f(x); }
; DI float lg2(float x) { return __builtin_amdgcn_logf(x); }
; template <int S> DI bf16x8 pack8(const f32x16& x) { u32x4 p; p[0] = cvtpk(x[8 * S], x[8 * S + 1]); p[1] = cvtpk(x[8 * S + 2], x[8 * S + 3]); p[2] = cvtpk(x[8 * S + 4], x[8 * S + 5]); p[3] = cvtpk(x[8 * S + 6], x[8 * S + 7]); return __builtin_bit_cast(bf16x8, p); }
; DI void sb_unit(LAS char* lds, int b, int h, int qb, const bf16_t* __restrict__ Q, const bf16_t* __restrict__ K, const bf16_t* __restrict__ VT, const bf16_t* __restrict__ G, bf16_t* __restrict__ MIX) {
;     ...
;                 { const float z = p0[r]; const float lg = (z > 30.f) ? z : lg2(1.0f + ex2(z)); const bool valid = !diag || (kv0 + crow(r, hi) < tq); L0[r] = valid ? -lg : 0.f; p0[r] = valid ? (z - lg) : -1e30f; }
;                 { const float z = p1[r]; const float lg = (z > 30.f) ? z : lg2(1.0f + ex2(z)); const bool valid = !diag || (kv0 + 32 + crow(r, hi) < tq); L1[r] = valid ? -lg : 0.f; p1[r] = valid ? (z - lg) : -1e30f; }
;             }
;             const bf16x8 Lh0 = pack8<0>(L0), Lh1 = pack8<1>(L0), Lh2 = pack8<0>(L1), Lh3 = pack8<1>(L1);
	v_cndmask_b32_e64 v202, 0, -v170, s[52:53]
	v_cndmask_b32_e64 v203, 0, -v171, s[54:55]
	v_cndmask_b32_e64 v204, 0, -v172, s[56:57]
	v_cndmask_b32_e64 v205, 0, -v173, s[58:59]
	v_cndmask_b32_e64 v206, 0, -v174, s[60:61]
	v_cndmask_b32_e64 v207, 0, -v175, s[62:63]
	v_cndmask_b32_e64 v208, 0, -v176, s[64:65]
	v_cndmask_b32_e64 v209, 0, -v177, s[66:67]
	v_cndmask_b32_e64 v210, 0, -v178, s[68:69]
	v_cndmask_b32_e64 v211, 0, -v179, s[70:71]
	v_sub_f32_e32 v170, v62, v170
	v_sub_f32_e32 v171, v63, v171
	v_sub_f32_e32 v172, v64, v172
	v_sub_f32_e32 v173, v65, v173
	v_sub_f32_e32 v174, v66, v174
	v_sub_f32_e32 v175, v67, v175
	v_sub_f32_e32 v176, v36, v176
	v_sub_f32_e32 v177, v37, v177
	v_sub_f32_e32 v178, v38, v178
	v_sub_f32_e32 v179, v39, v179
	v_cndmask_b32_e64 v129, v237, v170, s[52:53]
	v_cndmask_b32_e64 v131, v237, v171, s[54:55]
	v_cndmask_b32_e64 v133, v237, v172, s[56:57]
	v_cndmask_b32_e64 v135, v237, v173, s[58:59]
	v_cndmask_b32_e64 v66, v237, v174, s[60:61]
	v_cndmask_b32_e64 v155, v237, v175, s[62:63]
	v_cndmask_b32_e64 v110, v237, v176, s[64:65]
	v_cndmask_b32_e64 v112, v237, v177, s[66:67]
	v_cndmask_b32_e64 v114, v237, v178, s[68:69]
	v_cndmask_b32_e64 v116, v237, v179, s[70:71]
	v_add_u32_e32 v212, 40, v35
	v_add_u32_e32 v213, 41, v35
	v_add_u32_e32 v214, 42, v35
	v_add_u32_e32 v215, 43, v35
	v_add_u32_e32 v216, 48, v35
	v_add_u32_e32 v217, 49, v35
	v_add_u32_e32 v218, 50, v35
	v_add_u32_e32 v219, 51, v35
	v_add_u32_e32 v220, 56, v35
	v_add_u32_e32 v221, 57, v35
	v_cmp_lt_i32_e64 s[52:53], v212, v101
	v_cmp_lt_i32_e64 s[54:55], v213, v101
	v_cmp_lt_i32_e64 s[56:57], v214, v101
	v_cmp_lt_i32_e64 s[58:59], v215, v101
	v_cmp_lt_i32_e64 s[60:61], v216, v101
	v_cmp_lt_i32_e64 s[62:63], v217, v101
	v_cmp_lt_i32_e64 s[64:65], v218, v101
	v_cmp_lt_i32_e64 s[66:67], v219, v101
	v_cmp_lt_i32_e64 s[68:69], v220, v101
	v_cmp_lt_i32_e64 s[70:71], v221, v101
	v_cndmask_b32_e64 v212, 0, -v180, s[52:53]
	v_cndmask_b32_e64 v213, 0, -v181, s[54:55]
	v_cndmask_b32_e64 v214, 0, -v182, s[56:57]
	v_cndmask_b32_e64 v215, 0, -v183, s[58:59]
	v_cndmask_b32_e64 v216, 0, -v184, s[60:61]
	v_cndmask_b32_e64 v217, 0, -v185, s[62:63]
	v_cndmask_b32_e64 v218, 0, -v186, s[64:65]
	v_cndmask_b32_e64 v219, 0, -v187, s[66:67]
	v_cndmask_b32_e64 v220, 0, -v188, s[68:69]
	v_cndmask_b32_e64 v221, 0, -v189, s[70:71]
	v_sub_f32_e32 v180, v40, v180
	v_sub_f32_e32 v181, v41, v181
	v_sub_f32_e32 v182, v42, v182
	v_sub_f32_e32 v183, v43, v183
	v_sub_f32_e32 v184, v44, v184
	v_sub_f32_e32 v185, v45, v185
	v_sub_f32_e32 v186, v46, v186
	v_sub_f32_e32 v187, v47, v187
	v_sub_f32_e32 v188, v48, v188
	v_sub_f32_e32 v189, v49, v189
	v_cndmask_b32_e64 v118, v237, v180, s[52:53]
	v_cndmask_b32_e64 v120, v237, v181, s[54:55]
	v_cndmask_b32_e64 v122, v237, v182, s[56:57]
	v_cndmask_b32_e64 v124, v237, v183, s[58:59]
	v_cndmask_b32_e64 v126, v237, v184, s[60:61]
	v_cndmask_b32_e64 v128, v237, v185, s[62:63]
	v_cndmask_b32_e64 v130, v237, v186, s[64:65]
	v_cndmask_b32_e64 v132, v237, v187, s[66:67]
	v_cndmask_b32_e64 v134, v237, v188, s[68:69]
	v_cndmask_b32_e64 v136, v237, v189, s[70:71]
	v_add_u32_e32 v222, 58, v35
	v_add_u32_e32 v223, 59, v35
	v_cmp_lt_i32_e64 s[52:53], v222, v101
	v_cmp_lt_i32_e64 s[54:55], v223, v101
	s_nop 1
	v_cndmask_b32_e64 v222, 0, -v190, s[52:53]
	v_cndmask_b32_e64 v223, 0, -v191, s[54:55]
	v_sub_f32_e32 v190, v50, v190
	v_sub_f32_e32 v191, v51, v191
	v_cndmask_b32_e64 v154, v237, v190, s[52:53]
	v_cndmask_b32_e64 v156, v237, v191, s[54:55]
	v_mov_b32_e32 v109, v192
	v_cvt_pk_bf16_f32 v138, v192, v193
	v_cvt_pk_bf16_f32 v139, v194, v195
	v_cvt_pk_bf16_f32 v140, v196, v197
	v_cvt_pk_bf16_f32 v141, v198, v199
	v_cvt_pk_bf16_f32 v142, v200, v201
	v_cvt_pk_bf16_f32 v143, v202, v203
	v_cvt_pk_bf16_f32 v144, v204, v205
	v_cvt_pk_bf16_f32 v145, v206, v207
	v_cvt_pk_bf16_f32 v146, v208, v209
	v_cvt_pk_bf16_f32 v147, v210, v211
	v_cvt_pk_bf16_f32 v148, v212, v213
	v_cvt_pk_bf16_f32 v149, v214, v215
	v_cvt_pk_bf16_f32 v150, v216, v217
	v_cvt_pk_bf16_f32 v151, v218, v219
	v_cvt_pk_bf16_f32 v152, v220, v221
	v_cvt_pk_bf16_f32 v153, v222, v223
; #define MFMA32(a, b, c) __builtin_amdgcn_mfma_f32_32x32x16_bf16((a), (b), (c), 0, 0, 0)
; DI float ex2(float x) { return __builtin_amdgcn_exp2f(x); }
; template <int S> DI bf16x8 pack8(const f32x16& x) { u32x4 p; p[0] = cvtpk(x[8 * S], x[8 * S + 1]); p[1] = cvtpk(x[8 * S + 2], x[8 * S + 3]); p[2] = cvtpk(x[8 * S + 4], x[8 * S + 5]); p[3] = cvtpk(x[8 * S + 6], x[8 * S + 7]); return __builtin_bit_cast(bf16x8, p); }
; #define SB_PV(ks, pa) { const bf16x8 v0 = ldsv(Vt + off128(r32, 2 * (ks) + hi)), v1 = ldsv(Vt + off128(32 + r32, 2 * (ks) + hi)); o0 = MFMA32(v0, pa, o0); o1 = MFMA32(v1, pa, o1); }
; DI void sb_unit(LAS char* lds, int b, int h, int qb, const bf16_t* __restrict__ Q, const bf16_t* __restrict__ K, const bf16_t* __restrict__ VT, const bf16_t* __restrict__ G, bf16_t* __restrict__ MIX) {
;     ...
;             const bf16x8 Lh0 = pack8<0>(L0), Lh1 = pack8<1>(L0), Lh2 = pack8<0>(L1), Lh3 = pack8<1>(L1);
;             f32x16 C0 = splat16(carry), C1 = C0;
;             C0 = MFMA32(tp0, Lh0, C0); C0 = MFMA32(tp1, Lh1, C0); C0 = MFMA32(ones, Lh2, C0); C0 = MFMA32(ones, Lh3, C0);
;             C1 = MFMA32(tp0, Lh2, C1); C1 = MFMA32(tp1, Lh3, C1);
;             const float cn = C0[0] + L0[0];
;             carry = __shfl(cn, r32, 64);
; #pragma unroll
;             for (int r = 0; r < 16; ++r) { p0[r] = ex2(p0[r] + C0[r]); p1[r] = ex2(p1[r] + C1[r]); }
;             const bf16x8 pa0 = pack8<0>(p0), pa1 = pack8<1>(p0), pa2 = pack8<0>(p1), pa3 = pack8<1>(p1);
;     ...
;             SB_PV(0, pa0) SB_PV(1, pa1) SB_PV(2, pa2) SB_PV(3, pa3)
;     ...
;             done = __all(carry < -152.f) ? 1 : 0;
.Lsb_sp_join:
	s_mov_b32 s0, s4
	v_mov_b32_e32 v35, v34
	v_mov_b32_e32 v36, v34
	v_mov_b32_e32 v37, v34
	v_mov_b32_e32 v38, v34
	v_mov_b32_e32 v39, v34
	v_mov_b32_e32 v40, v34
	v_mov_b32_e32 v41, v34
	v_mov_b32_e32 v42, v34
	v_mov_b32_e32 v43, v34
	v_mov_b32_e32 v44, v34
	v_mov_b32_e32 v45, v34
	v_mov_b32_e32 v46, v34
	v_mov_b32_e32 v47, v34
	v_mov_b32_e32 v48, v34
	v_mov_b32_e32 v49, v34
	v_writelane_b32 v254, s0, 48
	s_nop 1
	v_mfma_f32_32x32x16_bf16 v[50:65], v[84:87], v[138:141], v[34:49]
	v_mov_b64_e32 v[140:141], s[6:7]
	v_mov_b64_e32 v[138:139], s[4:5]
	v_writelane_b32 v254, s1, 49
	v_writelane_b32 v254, s2, 50
	v_writelane_b32 v254, s3, 51
	s_mov_b32 s0, 0xc3180000
	v_mfma_f32_32x32x16_bf16 v[50:65], v[88:91], v[142:145], v[50:65]
	v_mfma_f32_32x32x16_bf16 v[34:49], v[84:87], v[146:149], v[34:49]
	v_mfma_f32_32x32x16_bf16 v[50:65], v[138:141], v[146:149], v[50:65]
	v_mfma_f32_32x32x16_bf16 v[34:49], v[88:91], v[150:153], v[34:49]
	v_mfma_f32_32x32x16_bf16 v[50:65], v[138:141], v[150:153], v[50:65]
	v_add3_u32 v192, s43, v104, v103
	v_add3_u32 v193, s43, v105, v103
	v_add3_u32 v194, s43, v106, v103
	v_add3_u32 v195, s43, v107, v103
	ds_read_b128 v[160:163], v192 offset:8192
	ds_read_b128 v[164:167], v192 offset:12288
	ds_read_b128 v[168:171], v193 offset:8192
	ds_read_b128 v[172:175], v193 offset:12288
	ds_read_b128 v[176:179], v194 offset:8192
	ds_read_b128 v[180:183], v194 offset:12288
	ds_read_b128 v[184:187], v195 offset:8192
	ds_read_b128 v[188:191], v195 offset:12288
	s_nop 0
	v_add_f32_e32 v38, v118, v38
	v_add_f32_e32 v39, v120, v39
	v_add_f32_e32 v40, v122, v40
	v_add_f32_e32 v42, v126, v42
	v_add_f32_e32 v43, v128, v43
	v_add_f32_e32 v44, v130, v44
	v_add_f32_e32 v45, v132, v45
	v_add_f32_e32 v46, v134, v46
	v_add_f32_e32 v67, v109, v50
	v_and_or_b32 v109, v238, 64, v100
	v_add_f32_e32 v50, v50, v108
	v_add_f32_e32 v54, v54, v117
	v_exp_f32_e32 v108, v38
	v_add_f32_e32 v38, v55, v119
	v_exp_f32_e32 v55, v39
	v_add_f32_e32 v39, v56, v121
	v_exp_f32_e32 v56, v40
	v_add_f32_e32 v40, v57, v123
	v_add_f32_e32 v57, v58, v125
	v_exp_f32_e32 v58, v42
	v_add_f32_e32 v42, v59, v127
	v_exp_f32_e32 v59, v43
	v_add_f32_e32 v43, v60, v129
	v_exp_f32_e32 v60, v44
	v_add_f32_e32 v44, v61, v131
	v_exp_f32_e32 v61, v45
	v_add_f32_e32 v45, v62, v133
	v_exp_f32_e32 v62, v46
	v_add_f32_e32 v46, v63, v135
	v_lshlrev_b32_e32 v109, 2, v109
	v_add_f32_e32 v51, v51, v111
	v_add_f32_e32 v52, v52, v113
	v_add_f32_e32 v53, v53, v115
	v_exp_f32_e32 v54, v54
	v_exp_f32_e32 v38, v38
	v_add_f32_e32 v41, v124, v41
	v_exp_f32_e32 v63, v46
	v_add_f32_e32 v46, v136, v47
	ds_bpermute_b32 v67, v109, v67
	v_exp_f32_e32 v50, v50
	v_exp_f32_e32 v51, v51
	v_exp_f32_e32 v52, v52
	v_exp_f32_e32 v53, v53
	v_exp_f32_e32 v39, v39
	v_exp_f32_e32 v40, v40
	v_exp_f32_e32 v41, v41
	v_exp_f32_e32 v57, v57
	v_exp_f32_e32 v42, v42
	v_exp_f32_e32 v109, v46
	v_add_f32_e32 v46, v64, v66
	v_exp_f32_e32 v64, v46
	v_add_f32_e32 v46, v154, v48
	v_exp_f32_e32 v66, v46
	v_add_f32_e32 v46, v65, v155
	v_exp_f32_e32 v65, v46
	v_add_f32_e32 v46, v156, v49
	v_cvt_pk_bf16_f32 v48, v54, v38
	v_add_f32_e32 v34, v110, v34
	v_exp_f32_e32 v110, v46
	v_cvt_pk_bf16_f32 v46, v50, v51
	v_cvt_pk_bf16_f32 v47, v52, v53
	v_cvt_pk_bf16_f32 v49, v39, v40
	v_cvt_pk_bf16_f32 v42, v57, v42
	v_cvt_pk_bf16_f32 v40, v108, v55
	v_cvt_pk_bf16_f32 v41, v56, v41
	s_waitcnt lgkmcnt(0)
	v_mfma_f32_32x32x16_bf16 v[18:33], v[160:163], v[46:49], v[18:33]
	v_exp_f32_e32 v43, v43
	v_exp_f32_e32 v44, v44
	v_exp_f32_e32 v45, v45
	v_add_f32_e32 v35, v112, v35
	v_add_f32_e32 v36, v114, v36
	v_cvt_pk_bf16_f32 v43, v43, v44
	s_waitcnt lgkmcnt(0)
	v_mfma_f32_32x32x16_bf16 v[2:17], v[164:167], v[46:49], v[2:17]
	v_cvt_pk_bf16_f32 v44, v45, v63
	v_cvt_pk_bf16_f32 v45, v64, v65
	v_add_f32_e32 v37, v116, v37
	v_exp_f32_e32 v34, v34
	v_exp_f32_e32 v35, v35
	v_exp_f32_e32 v36, v36
	s_waitcnt lgkmcnt(1)
	v_mfma_f32_32x32x16_bf16 v[18:33], v[168:171], v[42:45], v[18:33]
	v_exp_f32_e32 v37, v37
	v_cvt_pk_bf16_f32 v38, v34, v35
	v_cvt_pk_bf16_f32 v34, v58, v59
	v_cvt_pk_bf16_f32 v35, v60, v61
	v_cvt_pk_bf16_f32 v39, v36, v37
	v_cvt_pk_bf16_f32 v36, v62, v109
	s_waitcnt lgkmcnt(0)
	v_mfma_f32_32x32x16_bf16 v[2:17], v[172:175], v[42:45], v[2:17]
	v_cvt_pk_bf16_f32 v37, v66, v110
	v_cmp_gt_f32_e32 vcc, s0, v67
	s_cmp_eq_u64 vcc, exec
	s_cselect_b64 s[0:1], -1, 0
	s_waitcnt lgkmcnt(1)
	v_mfma_f32_32x32x16_bf16 v[18:33], v[176:179], v[38:41], v[18:33]
	s_waitcnt lgkmcnt(0)
	v_mfma_f32_32x32x16_bf16 v[2:17], v[180:183], v[38:41], v[2:17]
	s_waitcnt lgkmcnt(1)
	v_mfma_f32_32x32x16_bf16 v[18:33], v[184:187], v[34:37], v[18:33]
	s_waitcnt lgkmcnt(0)
	v_mfma_f32_32x32x16_bf16 v[2:17], v[188:191], v[34:37], v[2:17]
	v_cndmask_b32_e64 v36, 0, 1, s[0:1]
	v_mov_b32_e32 v34, v67
